# attention mainloop: one static s_setprio 1 for waves 4-7 (doc 7.4), reset after the unit loop; on top of v77
# baseline (speedup 1.0000x reference)
; #define LAS __attribute__((address_space(3)))
; __device__ __forceinline__ void attn_phase(const Args& a, int layer, LAS unsigned char* lds, int tid, int wave, int lane) {
;     unsigned char* cb = a.ws + WS_CR;
;     const bf16_t* QR = (const bf16_t*)(cb + C_QR); const bf16_t* KR = (const bf16_t*)(cb + C_KR); const bf16_t* VT = (const bf16_t*)(cb + C_VT); bf16_t* YS = (bf16_t*)(cb + C_YS);
;     const int half = lane >> 5, r31 = lane & 31;
;     const float sc2 = 0.08838834764831845f * LOG2E;
;     const int nunits = layer == 1 ? 1024 : 1024 + 32;
;     const int krow_s = tid >> 4, kc_s = tid & 15, vrow_s = tid >> 2, vc_s = tid & 3;
;     const int G_ = gridDim.x, nr = (1024 + G_ - 1) / G_;
;     for (int it = 0; ; ++it) {
;         int u;
;         if (it < nr) { u = blockIdx.x + it * G_; if (u >= 1024) continue; }
;         else { u = 1024 + (G_ - 1 - (int)blockIdx.x) + (it - nr) * G_; if (u >= nunits) break; }
;         int b, kvh, qb; bool isc;
;         if (u < 1024) { isc = false; b = u >> 8; kvh = (u >> 7) & 1; qb = u & 127; } else { const int uc = u - 1024; isc = true; b = uc >> 3; kvh = (uc >> 2) & 1; qb = uc & 3; }
;         const int th = wave & 1, g = wave >> 1, hq = kvh * 4 + g, t0 = qb * 64, tq0 = t0 + th * 32;
;         const int qrow0 = isc ? b * CTXL : MC + b * SEQ;
;         const int klo = isc ? 0 : (t0 >= 128 ? -4 : -(t0 >> 5)), khi = isc ? -1 : ((SEQ - t0) / 32 - 1 < 5 ? (SEQ - t0) / 32 - 1 : 5);
;         const int nloc = khi - klo + 1, nt = nloc + 8;
.LBB0_884:
	s_add_u32 s42, s50, 0x4de00000
	s_addc_u32 s43, s51, 0
	s_and_b64 s[2:3], s[84:85], exec
	s_movk_i32 s1, 0x420
	s_cselect_b32 s1, s1, 0x400
	s_abs_i32 s3, s60
	v_cvt_f32_u32_e32 v3, s3
	s_sub_i32 s8, 0, s3
	s_add_i32 s2, s60, 0x3ff
	s_abs_i32 s7, s2
	v_rcp_iflag_f32_e32 v3, v3
	s_xor_b32 s5, s2, s60
	s_ashr_i32 s5, s5, 31
	v_ashrrev_i32_e32 v2, 4, v131
	v_mul_f32_e32 v3, 0x4f7ffffe, v3
	v_cvt_u32_f32_e32 v3, v3
	v_readlane_b32 s12, v254, 42
	v_readlane_b32 s13, v254, 43
	v_lshlrev_b32_e32 v8, 4, v152
	v_readfirstlane_b32 s9, v3
	s_mul_i32 s8, s8, s9
	s_mul_hi_u32 s8, s9, s8
	s_add_i32 s9, s9, s8
	s_mul_hi_u32 s8, s7, s9
	s_mul_i32 s9, s8, s3
	s_sub_i32 s7, s7, s9
	s_add_i32 s9, s8, 1
	s_sub_i32 s11, s7, s3
	s_cmp_ge_u32 s7, s3
	s_cselect_b32 s8, s9, s8
	v_ashrrev_i32_e32 v3, 31, v2
	s_cselect_b32 s7, s11, s7
	s_add_i32 s9, s8, 1
	v_lshlrev_b64 v[6:7], 9, v[2:3]
	s_cmp_ge_u32 s7, s3
	v_lshl_add_u64 v[6:7], s[50:51], 0, v[6:7]
	v_mov_b32_e32 v9, v175
	s_cselect_b32 s3, s9, s8
	s_lshl_b32 s9, s12, 3
	v_lshl_add_u64 v[6:7], v[6:7], 0, v[8:9]
	s_mov_b64 s[12:13], 0x52000000
	v_and_b32_e32 v166, 48, v135
	v_mov_b32_e32 v167, v175
	v_lshl_add_u64 v[164:165], v[6:7], 0, s[12:13]
	v_lshl_add_u64 v[6:7], s[50:51], 0, v[166:167]
	s_mov_b64 s[12:13], 0x53080000
	s_xor_b32 s3, s3, s5
	v_lshl_add_u64 v[168:169], v[6:7], 0, s[12:13]
	s_movk_i32 s12, 0x110
	v_lshrrev_b32_e32 v5, 5, v171
	v_ashrrev_i32_e32 v162, 2, v131
	s_sub_i32 s3, s3, s5
	s_bfe_u32 s5, s20, 0x10006
	v_mul_lo_u32 v2, v2, s12
	s_movk_i32 s11, 0x48
	v_and_b32_e32 v177, 31, v131
	s_lshl_b32 s8, s5, 5
	v_lshlrev_b32_e32 v4, 3, v5
	v_cmp_gt_u32_e32 vcc, 32, v171
	v_add_u32_e32 v2, 0, v2
	v_mul_lo_u32 v3, v162, s11
	v_lshlrev_b32_e32 v170, 2, v5
	s_sub_i32 s11, s60, s96
	s_mov_b32 s2, 0
	s_ashr_i32 s7, s20, 7
	v_cndmask_b32_e64 v178, 0, 1.0, vcc
	v_ashrrev_i32_e32 v163, 31, v162
	v_add_u32_e32 v167, 0, v3
	v_add_u32_e32 v179, 0, v4
	v_lshlrev_b32_e32 v186, 4, v5
	v_mul_u32_u24_e32 v187, 0x48, v177
	v_mad_u32_u24 v188, v177, s12, 0
	v_or_b32_e32 v189, 1, v170
	v_or_b32_e32 v190, 2, v170
	v_or_b32_e32 v191, 3, v170
	v_or_b32_e32 v192, 8, v170
	v_or_b32_e32 v193, 9, v170
	v_or_b32_e32 v194, 10, v170
	v_or_b32_e32 v195, 11, v170
	v_or_b32_e32 v196, 16, v170
	v_or_b32_e32 v197, 17, v170
	v_or_b32_e32 v198, 18, v170
	v_or_b32_e32 v199, 19, v170
	v_or_b32_e32 v200, 24, v170
	v_or_b32_e32 v201, 25, v170
	v_or_b32_e32 v202, 26, v170
	v_or_b32_e32 v203, 27, v170
	s_addk_i32 s11, 0x3ff
	v_or_b32_e32 v204, s8, v177
	s_sub_i32 s12, 0, s5
	v_lshlrev_b32_e32 v174, 1, v4
	v_add_u32_e32 v205, v2, v8
	v_readfirstlane_b32 s98, v0
	s_nop 3
	s_lshr_b32 s98, s98, 6
	s_cmp_ge_u32 s98, 4
	s_cbranch_scc0 .Lattn_prio_done
	s_setprio 1
.Lattn_prio_done:
	s_branch .LBB0_886

; #define LAS __attribute__((address_space(3)))
; #define GAS __attribute__((address_space(1)))
; #define LDS_WAIT() asm volatile("s_waitcnt lgkmcnt(0)" ::: "memory")
; __device__ __forceinline__ void transpose_item(const float* W, int K, int N, bf16_t* WT, int k0, int n0, int drow0, LAS float* scr, int lane) {
;     f32x4 v[8];
; #pragma unroll
;     for (int j = 0; j < 8; ++j) v[j] = *(const f32x4*)(W + (size_t)(k0 + (lane >> 3) + 8 * j) * N + n0 + 4 * (lane & 7));
; #pragma unroll
;     for (int j = 0; j < 8; ++j) { LAS float* d = scr + ((lane >> 3) + 8 * j) * 33 + 4 * (lane & 7); d[0] = v[j].x; d[1] = v[j].y; d[2] = v[j].z; d[3] = v[j].w; }
;     LDS_WAIT(); asm volatile("" ::: "memory");
;     const int c = lane & 7;
; #pragma unroll
;     for (int j = 0; j < 4; ++j) { const int n = (lane >> 3) + 8 * j; const LAS float* s = scr + (8 * c) * 33 + n;
;         u32x4 o; o.x = pk2(s[0 * 33], s[1 * 33]); o.y = pk2(s[2 * 33], s[3 * 33]); o.z = pk2(s[4 * 33], s[5 * 33]); o.w = pk2(s[6 * 33], s[7 * 33]);
;         *(GAS u32x4*)(WT + (size_t)(drow0 + n) * K + k0 + 8 * c) = o; }
;     LDS_WAIT(); asm volatile("" ::: "memory");
; }
; __device__ __forceinline__ void transpose_matrix(const float* W, int K, int N, bf16_t* WT, int rowmode, LAS float* scr, int gw, int ngw, int lane) {
;     const int nblk = N / 32, nitems = (K / 64) * nblk;
;     for (int it = gw; it < nitems; it += ngw) {
;         const int kb = it / nblk, nb = it - kb * nblk, n0 = 32 * nb;
;         int drow0 = n0;
;         if (rowmode == 1) { const int up = n0 >= DFF, j0 = up ? n0 - DFF : n0; drow0 = 256 * (j0 >> 7) + 128 * up + (j0 & 127); }
;         if (rowmode == 2 && n0 >= 5120 && n0 < 6400) {
;             const int tb = 5120 + (((n0 - 5120) >> 8) << 8), hh = ((n0 - tb) >> 7) & 1, d0 = (n0 - tb) & 127; drow0 = tb + ((d0 & 32) ? 128 : 0) + hh * 64 + ((d0 >> 6) << 5); }
;         if (rowmode == 2 && n0 >= 3072 && n0 < 5120) { const int wh = n0 >= 4096, j0 = n0 - 3072 - wh * 1024; drow0 = 3072 + 256 * (j0 >> 7) + 128 * wh + (j0 & 127); }
;         transpose_item(W, K, N, WT, 64 * kb, n0, drow0, scr, lane);
; __global__ void __launch_bounds__(NWAVES * 64, 2) fwd_kernel(Args a_param) {
;     ...
;             if (cvt1 && !cvfirst) { __syncthreads(); convert_weights(a, 1, lds, gw, ngw, wave, lane); }
.LBB0_937:
	s_setprio 0
	v_readlane_b32 s2, v253, 26
	v_readlane_b32 s3, v253, 27
	s_and_b64 s[2:3], s[2:3], s[84:85]
	s_and_b64 vcc, exec, s[2:3]
	s_cbranch_vccz .LBB0_971
	v_readlane_b32 s1, v254, 63
	s_lshl_b32 s1, s1, 14
	s_add_i32 s3, s1, 0
	v_readlane_b32 s1, v254, 50
	s_cmpk_lt_i32 s1, 0x2b00
	v_lshlrev_b32_e32 v2, 4, v171
	v_lshlrev_b32_e32 v38, 3, v171
	s_cselect_b64 s[38:39], -1, 0
	s_cmpk_gt_i32 s1, 0x2aff
	s_waitcnt vmcnt(2)
	v_lshrrev_b32_e32 v32, 3, v171
	v_and_b32_e32 v174, 0x70, v2
	s_waitcnt vmcnt(1)
	v_and_b32_e32 v26, 56, v38
	s_barrier
	s_cbranch_scc1 .LBB0_941
	v_readlane_b32 s12, v254, 59
	v_readlane_b32 s13, v254, 60
	s_mov_b64 s[8:9], 0x5600000
	v_lshrrev_b32_e32 v27, 3, v171
	v_lshl_add_u64 v[2:3], s[12:13], 0, v[174:175]
	v_lshl_add_u64 v[28:29], v[2:3], 0, s[8:9]
	v_lshlrev_b32_e32 v2, 1, v26
	v_mov_b32_e32 v3, v175
	v_lshl_add_u64 v[2:3], s[50:51], 0, v[2:3]
	s_mov_b64 s[8:9], 0xdc00000
	v_add_u32_e32 v4, s3, v174
	v_mul_u32_u24_e32 v5, 0x84, v27
	v_mul_u32_u24_e32 v6, 0x84, v26
	v_lshl_add_u64 v[30:31], v[2:3], 0, s[8:9]
	v_lshlrev_b32_e32 v2, 2, v27
	v_readlane_b32 s5, v254, 50
	v_or_b32_e32 v33, 8, v27
	v_or_b32_e32 v34, 16, v27
	v_or_b32_e32 v35, 24, v27
	v_add3_u32 v36, s3, v6, v2
	s_lshl_b32 s1, s5, 5
	s_lshl_b32 s2, s60, 8
	v_add_u32_e32 v37, v4, v5
	v_readlane_b32 s14, v254, 61
	v_readlane_b32 s15, v254, 62
